# pool-matrix conversion items moved to the least-loaded waves (phase 0: waves 1408+, scan converter: waves 768+)
# speedup vs baseline: 1.0049x; 1.0049x over previous
; #define LAS __attribute__((address_space(3)))
; template <int MODE>
; DI void cvt_matrix(const float* W, int ldw, int nvalid, int K, int Npad, bf16_t* WT, LAS float* scr, int gw, int NGW, int lane) {
;     const int nblk = Npad / 32, nitems = (K / 64) * nblk;
;     for (int it = gw; it < nitems; it += NGW) {
;         const int kb = it / nblk, nb = it % nblk; int src0 = nb * 32;
;         if (MODE == 1) { const int pn = nb >> 3, wb = nb & 7; src0 = (wb < 4) ? pn * 128 + wb * 32 : FF + pn * 128 + (wb - 4) * 32; }
;         cvt_item(W, ldw, nvalid, src0, WT, K, nb * 32, kb * 64, scr, lane);
;     }
; }
; DI void convert_layer_weights(const Params& p, int layer, LAS float* scr, int gw, int NGW, int lane) {
;     cvt_matrix<1>(p.in[21] + (size_t)layer * D * NUP, NUP, NUP, D, NUP, (bf16_t*)(p.ws + w_up(layer)), scr, gw, NGW, lane);
;     cvt_matrix<0>(p.in[24] + (size_t)layer * FF * D, D, D, FF, D, (bf16_t*)(p.ws + w_dn(layer)), scr, gw, NGW, lane);
;     if (layer == 0 || layer == 3) {
;         for (int g = 0; g < 4; ++g) cvt_matrix<0>(p.in[11] + (size_t)((layer / 3) * 4 + g) * 65536, 256, 256, 256, 256, (bf16_t*)(p.ws + w_mix(layer)) + (size_t)g * 65536, scr, gw, NGW, lane);
.LBB0_784:
	s_lshl_b32 s8, s15, 5
	s_sub_i32 s8, s12, s8
	s_addk_i32 s8, 0xfd00
	s_cmp_lt_u32 s8, 32
	s_cbranch_scc0 .LBB0_783
	s_lshl_b32 s8, s15, 16
	v_readlane_b32 s60, v254, 7
	s_lshl_b64 s[4:5], s[8:9], 2
	v_readlane_b32 s66, v254, 13
	v_readlane_b32 s67, v254, 14
	s_add_u32 s4, s66, s4
	s_addc_u32 s5, s67, s5
	s_add_u32 s4, s4, 0x100000
	s_addc_u32 s5, s5, 0
	s_lshl_b32 s8, s15, 17
	v_lshl_add_u64 v[2:3], v[0:1], 0, s[8:9]
	s_lshl_b32 s8, s15, 5
	s_sub_i32 s8, s12, s8
	s_addk_i32 s8, 0xfd00
	v_readlane_b32 s61, v254, 8
	v_readlane_b32 s62, v254, 9
	v_readlane_b32 s63, v254, 10
	v_readlane_b32 s64, v254, 11
	v_readlane_b32 s65, v254, 12
	v_readlane_b32 s68, v254, 15
	v_readlane_b32 s69, v254, 16
	v_readlane_b32 s70, v254, 17
	v_readlane_b32 s71, v254, 18
	v_readlane_b32 s72, v254, 19
	v_readlane_b32 s73, v254, 20
	v_readlane_b32 s74, v254, 21
	v_readlane_b32 s75, v254, 22
	s_branch .LBB0_787

; #define LAS __attribute__((address_space(3)))
; template <int MODE>
; DI void cvt_matrix(const float* W, int ldw, int nvalid, int K, int Npad, bf16_t* WT, LAS float* scr, int gw, int NGW, int lane) {
;     const int nblk = Npad / 32, nitems = (K / 64) * nblk;
;     for (int it = gw; it < nitems; it += NGW) {
;         const int kb = it / nblk, nb = it % nblk; int src0 = nb * 32;
;         if (MODE == 1) { const int pn = nb >> 3, wb = nb & 7; src0 = (wb < 4) ? pn * 128 + wb * 32 : FF + pn * 128 + (wb - 4) * 32; }
;         cvt_item(W, ldw, nvalid, src0, WT, K, nb * 32, kb * 64, scr, lane);
;     }
; }
; DI void convert_layer_weights(const Params& p, int layer, LAS float* scr, int gw, int NGW, int lane) {
;     cvt_matrix<1>(p.in[21] + (size_t)layer * D * NUP, NUP, NUP, D, NUP, (bf16_t*)(p.ws + w_up(layer)), scr, gw, NGW, lane);
;     cvt_matrix<0>(p.in[24] + (size_t)layer * FF * D, D, D, FF, D, (bf16_t*)(p.ws + w_dn(layer)), scr, gw, NGW, lane);
;     if (layer == 0 || layer == 3) {
;         for (int g = 0; g < 4; ++g) cvt_matrix<0>(p.in[11] + (size_t)((layer / 3) * 4 + g) * 65536, 256, 256, 256, 256, (bf16_t*)(p.ws + w_mix(layer)) + (size_t)g * 65536, scr, gw, NGW, lane);
.LBB0_1561:
	s_lshl_b32 s8, s17, 5
	s_sub_i32 s8, s28, s8
	s_addk_i32 s8, 0xfa80
	s_cmp_lt_u32 s8, 32
	s_cbranch_scc0 .LBB0_1560
	s_lshl_b32 s6, s17, 16
	s_add_i32 s8, s6, s18
	v_readlane_b32 s60, v254, 7
	s_lshl_b64 s[6:7], s[8:9], 2
	v_readlane_b32 s66, v254, 13
	v_readlane_b32 s67, v254, 14
	s_add_u32 s6, s66, s6
	s_addc_u32 s7, s67, s7
	s_lshl_b32 s8, s17, 17
	v_lshl_add_u64 v[2:3], v[0:1], 0, s[8:9]
	s_lshl_b32 s8, s17, 5
	s_sub_i32 s8, s28, s8
	s_addk_i32 s8, 0xfa80
	v_readlane_b32 s61, v254, 8
	v_readlane_b32 s62, v254, 9
	v_readlane_b32 s63, v254, 10
	v_readlane_b32 s64, v254, 11
	v_readlane_b32 s65, v254, 12
	v_readlane_b32 s68, v254, 15
	v_readlane_b32 s69, v254, 16
	v_readlane_b32 s70, v254, 17
	v_readlane_b32 s71, v254, 18
	v_readlane_b32 s72, v254, 19
	v_readlane_b32 s73, v254, 20
	v_readlane_b32 s74, v254, 21
	v_readlane_b32 s75, v254, 22
	s_branch .LBB0_1564
